# SwiGLU epilogue: rs^2 folded through a per-row reciprocal, multiply+add replaced by one fma per element (f32 math)
# speedup vs baseline: 1.0033x; 1.0033x over previous
.LBB0_1068:
	s_lshl_b32 s9, s54, 8
	s_add_i32 s9, s9, s27
	v_or_b32_e32 v154, s9, v157
	v_ashrrev_i32_e32 v155, 31, v154
	v_or_b32_e32 v150, 16, v154
	v_lshlrev_b64 v[146:147], 6, v[154:155]
	v_ashrrev_i32_e32 v151, 31, v150
	v_or_b32_e32 v158, 32, v154
	v_lshl_add_u64 v[146:147], v[136:137], 0, v[146:147]
	v_lshlrev_b64 v[150:151], 6, v[150:151]
	v_ashrrev_i32_e32 v159, 31, v158
	global_load_dwordx4 v[146:149], v[146:147], off
	v_lshl_add_u64 v[150:151], v[136:137], 0, v[150:151]
	v_lshlrev_b64 v[158:159], 6, v[158:159]
	global_load_dwordx4 v[150:153], v[150:151], off
	v_lshl_add_u64 v[158:159], v[136:137], 0, v[158:159]
	global_load_dwordx4 v[178:181], v[158:159], off
	v_or_b32_e32 v158, 48, v154
	v_ashrrev_i32_e32 v159, 31, v158
	v_lshlrev_b64 v[158:159], 6, v[158:159]
	v_lshl_add_u64 v[158:159], v[136:137], 0, v[158:159]
	global_load_dwordx4 v[190:193], v[158:159], off
	v_add_u32_e32 v158, 0x80, v154
	v_ashrrev_i32_e32 v159, 31, v158
	v_lshlrev_b64 v[158:159], 6, v[158:159]
	v_lshl_add_u64 v[158:159], v[136:137], 0, v[158:159]
	global_load_dwordx4 v[194:197], v[158:159], off
	v_add_u32_e32 v158, 0x90, v154
	v_ashrrev_i32_e32 v159, 31, v158
	v_lshlrev_b64 v[158:159], 6, v[158:159]
	v_lshl_add_u64 v[158:159], v[136:137], 0, v[158:159]
	global_load_dwordx4 v[198:201], v[158:159], off
	v_add_u32_e32 v158, 0xa0, v154
	v_add_u32_e32 v154, 0xb0, v154
	v_ashrrev_i32_e32 v159, 31, v158
	v_ashrrev_i32_e32 v155, 31, v154
	v_lshlrev_b64 v[158:159], 6, v[158:159]
	v_lshlrev_b64 v[154:155], 6, v[154:155]
	v_lshl_add_u64 v[158:159], v[136:137], 0, v[158:159]
	v_lshl_add_u64 v[154:155], v[136:137], 0, v[154:155]
	global_load_dwordx4 v[202:205], v[158:159], off
	global_load_dwordx4 v[206:209], v[154:155], off
	v_and_b32_e32 v156, 64, v213
	v_xor_b32_e32 v145, 16, v213
	v_add_u32_e32 v156, 64, v156
	v_cmp_lt_i32_e32 vcc, v145, v156
	s_mov_b64 s[56:57], s[44:45]
	s_mov_b32 s55, s72
	v_cndmask_b32_e32 v145, v213, v145, vcc
	v_lshlrev_b32_e32 v165, 2, v145
	v_xor_b32_e32 v145, 32, v213
	v_cmp_lt_i32_e32 vcc, v145, v156
	s_waitcnt vmcnt(0)
	v_mov_b32_e32 v154, v147
	v_mov_b32_e32 v155, v148
	v_mov_b32_e32 v147, v149
	v_pk_add_f32 v[162:163], v[154:155], v[146:147]
	v_mov_b32_e32 v146, v151
	v_mov_b32_e32 v147, v152
	v_mov_b32_e32 v151, v153
	v_pk_add_f32 v[166:167], v[146:147], v[150:151]
	v_mov_b32_e32 v146, v179
	v_mov_b32_e32 v147, v180
	v_mov_b32_e32 v179, v181
	v_pk_add_f32 v[154:155], v[146:147], v[178:179]
	v_mov_b32_e32 v178, v166
	v_mov_b32_e32 v179, v162
	v_mov_b32_e32 v162, v167
	v_pk_add_f32 v[162:163], v[178:179], v[162:163]
	ds_bpermute_b32 v167, v165, v163
	ds_bpermute_b32 v166, v165, v162
	v_cndmask_b32_e32 v145, v213, v145, vcc
	v_lshlrev_b32_e32 v145, 2, v145
	v_mov_b32_e32 v146, v191
	v_mov_b32_e32 v147, v192
	s_waitcnt lgkmcnt(0)
	v_pk_add_f32 v[162:163], v[162:163], v[166:167]
	ds_bpermute_b32 v167, v145, v163
	ds_bpermute_b32 v166, v145, v162
	v_mov_b32_e32 v191, v193
	v_pk_add_f32 v[158:159], v[146:147], v[190:191]
	v_mov_b32_e32 v146, v195
	v_mov_b32_e32 v147, v196
	s_waitcnt lgkmcnt(0)
	v_pk_add_f32 v[166:167], v[162:163], v[166:167]
	v_mov_b64_e32 v[162:163], s[64:65]
	v_pk_fma_f32 v[166:167], v[166:167], s[28:29], v[162:163] op_sel_hi:[1,0,0]
	v_mov_b32_e32 v195, v197
	v_mul_f32_e32 v156, 0x4b800000, v167
	v_cmp_gt_f32_e64 s[0:1], s52, v167
	v_cmp_gt_f32_e32 vcc, s52, v166
	v_pk_add_f32 v[150:151], v[146:147], v[194:195]
	v_cndmask_b32_e64 v156, v167, v156, s[0:1]
	v_rsq_f32_e32 v156, v156
	v_mov_b32_e32 v146, v199
	v_mov_b32_e32 v147, v200
	v_mov_b32_e32 v199, v201
	v_mul_f32_e32 v160, 0x45800000, v156
	v_cndmask_b32_e64 v160, v156, v160, s[0:1]
	v_mul_f32_e32 v156, 0x4b800000, v166
	v_cndmask_b32_e32 v156, v166, v156, vcc
	v_rsq_f32_e32 v156, v156
	v_pk_add_f32 v[152:153], v[146:147], v[198:199]
	v_mov_b32_e32 v146, v203
	v_mov_b32_e32 v147, v204
	v_mul_f32_e32 v166, 0x45800000, v156
	v_mov_b32_e32 v203, v205
	v_mov_b32_e32 v148, v207
	v_mov_b32_e32 v149, v208
	v_mov_b32_e32 v207, v209
	v_cndmask_b32_e32 v156, v156, v166, vcc
	v_mov_b32_e32 v166, v158
	v_mov_b32_e32 v167, v154
	v_mov_b32_e32 v154, v159
	v_pk_add_f32 v[146:147], v[146:147], v[202:203]
	v_pk_add_f32 v[148:149], v[148:149], v[206:207]
	v_pk_add_f32 v[154:155], v[166:167], v[154:155]
	v_mov_b32_e32 v166, v152
	v_mov_b32_e32 v167, v150
	v_mov_b32_e32 v150, v153
	v_pk_add_f32 v[150:151], v[166:167], v[150:151]
	v_mov_b32_e32 v166, v148
	v_mov_b32_e32 v167, v146
	v_mov_b32_e32 v146, v149
	v_pk_add_f32 v[146:147], v[166:167], v[146:147]
	ds_bpermute_b32 v159, v165, v155
	ds_bpermute_b32 v158, v165, v154
	ds_bpermute_b32 v153, v165, v151
	ds_bpermute_b32 v152, v165, v150
	ds_bpermute_b32 v149, v165, v147
	ds_bpermute_b32 v148, v165, v146
	s_waitcnt lgkmcnt(4)
	v_pk_add_f32 v[154:155], v[154:155], v[158:159]
	ds_bpermute_b32 v159, v145, v155
	s_waitcnt lgkmcnt(3)
	v_pk_add_f32 v[150:151], v[150:151], v[152:153]
	ds_bpermute_b32 v158, v145, v154
	s_waitcnt lgkmcnt(2)
	v_pk_add_f32 v[146:147], v[146:147], v[148:149]
	ds_bpermute_b32 v153, v145, v151
	ds_bpermute_b32 v152, v145, v150
	ds_bpermute_b32 v149, v145, v147
	ds_bpermute_b32 v148, v145, v146
	s_waitcnt lgkmcnt(4)
	v_pk_add_f32 v[154:155], v[154:155], v[158:159]
	s_waitcnt lgkmcnt(2)
	v_pk_add_f32 v[150:151], v[150:151], v[152:153]
	v_pk_fma_f32 v[154:155], v[154:155], s[28:29], v[162:163] op_sel_hi:[1,0,0]
	s_waitcnt lgkmcnt(0)
	v_pk_add_f32 v[146:147], v[146:147], v[148:149]
	v_pk_fma_f32 v[150:151], v[150:151], s[28:29], v[162:163] op_sel_hi:[1,0,0]
	v_pk_fma_f32 v[146:147], v[146:147], s[28:29], v[162:163] op_sel_hi:[1,0,0]
	v_mul_f32_e32 v158, 0x4b800000, v155
	v_cmp_gt_f32_e64 s[0:1], s52, v155
	v_mul_f32_e32 v152, 0x4b800000, v151
	s_nop 0
	v_cndmask_b32_e64 v155, v155, v158, s[0:1]
	v_rsq_f32_e32 v155, v155
	v_mul_f32_e32 v145, 0x4b800000, v147
	v_mul_f32_e32 v158, 0x45800000, v155
	v_cndmask_b32_e64 v158, v155, v158, s[0:1]
	v_cmp_gt_f32_e64 s[0:1], s52, v151
	v_cmp_gt_f32_e32 vcc, s52, v154
	s_nop 0
	v_cndmask_b32_e64 v151, v151, v152, s[0:1]
	v_rsq_f32_e32 v151, v151
	v_mul_f32_e32 v155, 0x4b800000, v154
	v_mul_f32_e32 v152, 0x45800000, v151
	v_cndmask_b32_e64 v152, v151, v152, s[0:1]
	v_cmp_gt_f32_e64 s[0:1], s52, v147
	s_nop 1
	v_cndmask_b32_e64 v145, v147, v145, s[0:1]
	v_rsq_f32_e32 v145, v145
	v_cndmask_b32_e32 v154, v154, v155, vcc
	v_mul_f32_e32 v236, 0xbfb8aa3b, v160
	v_mul_f32_e32 v237, v160, v160
	v_rcp_f32_e32 v237, v237
	v_mul_f32_e32 v220, v236, v124
	v_mul_f32_e32 v222, v236, v125
	v_mul_f32_e32 v224, v236, v126
	v_mul_f32_e32 v226, v236, v127
	v_mul_f32_e32 v221, v124, v120
	v_mul_f32_e32 v223, v125, v121
	v_mul_f32_e32 v225, v126, v122
	v_mul_f32_e32 v227, v127, v123
	v_exp_f32_e32 v220, v220
	v_exp_f32_e32 v222, v222
	v_exp_f32_e32 v224, v224
	v_exp_f32_e32 v226, v226
	v_fma_f32 v220, v220, v237, v237
	v_fma_f32 v222, v222, v237, v237
	v_fma_f32 v224, v224, v237, v237
	v_fma_f32 v226, v226, v237, v237
	v_rcp_f32_e32 v220, v220
	v_rcp_f32_e32 v222, v222
	v_rcp_f32_e32 v224, v224
	v_rcp_f32_e32 v226, v226
	v_mul_f32_e32 v124, v221, v220
	v_mul_f32_e32 v125, v223, v222
	v_mul_f32_e32 v126, v225, v224
	v_mul_f32_e32 v122, v227, v226
	v_mul_f32_e32 v147, 0x45800000, v145
	v_cndmask_b32_e64 v148, v145, v147, s[0:1]
	s_lshl_b32 s0, s36, 7
	s_or_b32 s0, s0, s34
	s_ashr_i32 s11, s0, 6
	s_ashr_i32 s0, s9, 8
	s_mul_i32 s0, s0, 44
	s_add_i32 s0, s0, s11
	s_lshl_b32 s0, s0, 1
	s_or_b32 s0, s0, s87
	s_ashr_i32 s1, s0, 31
	s_lshl_b64 s[0:1], s[0:1], 14
	v_rsq_f32_e32 v154, v154
	s_nop 0
	v_mul_f32_e32 v155, 0x45800000, v154
	v_cndmask_b32_e32 v154, v154, v155, vcc
	v_cmp_gt_f32_e32 vcc, s52, v150
	v_mul_f32_e32 v151, 0x4b800000, v150
	s_nop 0
	v_cndmask_b32_e32 v150, v150, v151, vcc
	v_rsq_f32_e32 v150, v150
	s_addk_i32 s9, 0x80
	v_mul_f32_e32 v151, 0x45800000, v150
	v_cndmask_b32_e32 v150, v150, v151, vcc
	v_cmp_gt_f32_e32 vcc, s52, v146
	v_mul_f32_e32 v145, 0x4b800000, v146
	s_nop 0
	v_cndmask_b32_e32 v145, v146, v145, vcc
	v_rsq_f32_e32 v145, v145
	v_mul_f32_e32 v228, v236, v116
	v_mul_f32_e32 v230, v236, v117
	v_mul_f32_e32 v232, v236, v118
	v_mul_f32_e32 v234, v236, v119
	v_mul_f32_e32 v229, v116, v112
	v_mul_f32_e32 v231, v117, v113
	v_mul_f32_e32 v233, v118, v114
	v_mul_f32_e32 v235, v119, v115
	v_exp_f32_e32 v228, v228
	v_exp_f32_e32 v230, v230
	v_exp_f32_e32 v232, v232
	v_exp_f32_e32 v234, v234
	v_fma_f32 v228, v228, v237, v237
	v_fma_f32 v230, v230, v237, v237
	v_fma_f32 v232, v232, v237, v237
	v_fma_f32 v234, v234, v237, v237
	v_rcp_f32_e32 v228, v228
	v_rcp_f32_e32 v230, v230
	v_rcp_f32_e32 v232, v232
	v_rcp_f32_e32 v234, v234
	v_mul_f32_e32 v116, v229, v228
	v_mul_f32_e32 v117, v231, v230
	v_mul_f32_e32 v118, v233, v232
	v_mul_f32_e32 v112, v235, v234
	v_cvt_pk_bf16_f32 v114, v124, v125
	v_cvt_pk_bf16_f32 v115, v126, v122
	v_cvt_pk_bf16_f32 v116, v116, v117
	v_mul_f32_e32 v146, 0x45800000, v145
	v_cndmask_b32_e32 v146, v145, v146, vcc
	v_mov_b32_e32 v145, v169
	v_cvt_pk_bf16_f32 v117, v118, v112
	v_lshl_add_u64 v[112:113], v[138:139], 0, s[0:1]
	global_store_dwordx4 v[112:113], v[114:117], off
	s_ashr_i32 s0, s9, 8
	s_mul_i32 s0, s0, 44
	s_add_i32 s0, s0, s11
	s_lshl_b32 s0, s0, 1
	s_or_b32 s0, s0, s87
	s_ashr_i32 s1, s0, 31
	s_and_b32 s9, s9, 0xc0
	s_lshl_b64 s[0:1], s[0:1], 14
	s_add_u32 s0, s48, s0
	s_addc_u32 s1, s49, s1
	s_andn2_b64 vcc, exec, s[2:3]
	v_mul_f32_e32 v238, 0xbfb8aa3b, v156
	v_mul_f32_e32 v239, v156, v156
	v_rcp_f32_e32 v239, v239
	v_mul_f32_e32 v220, v238, v108
	v_mul_f32_e32 v222, v238, v109
	v_mul_f32_e32 v224, v238, v110
	v_mul_f32_e32 v226, v238, v111
	v_mul_f32_e32 v221, v108, v104
	v_mul_f32_e32 v223, v109, v105
	v_mul_f32_e32 v225, v110, v106
	v_mul_f32_e32 v227, v111, v107
	v_exp_f32_e32 v220, v220
	v_exp_f32_e32 v222, v222
	v_exp_f32_e32 v224, v224
	v_exp_f32_e32 v226, v226
	v_fma_f32 v220, v220, v239, v239
	v_fma_f32 v222, v222, v239, v239
	v_fma_f32 v224, v224, v239, v239
	v_fma_f32 v226, v226, v239, v239
	v_rcp_f32_e32 v220, v220
	v_rcp_f32_e32 v222, v222
	v_rcp_f32_e32 v224, v224
	v_rcp_f32_e32 v226, v226
	v_mul_f32_e32 v108, v221, v220
	v_mul_f32_e32 v109, v223, v222
	v_mul_f32_e32 v110, v225, v224
	v_mul_f32_e32 v106, v227, v226
	s_nop 0
	s_nop 0
	s_nop 0
	v_mul_f32_e32 v228, v238, v100
	v_mul_f32_e32 v230, v238, v101
	v_mul_f32_e32 v232, v238, v102
	v_mul_f32_e32 v234, v238, v103
	v_mul_f32_e32 v229, v100, v96
	v_mul_f32_e32 v231, v101, v97
	v_mul_f32_e32 v233, v102, v98
	v_mul_f32_e32 v235, v103, v99
	v_exp_f32_e32 v228, v228
	v_exp_f32_e32 v230, v230
	v_exp_f32_e32 v232, v232
	v_exp_f32_e32 v234, v234
	v_fma_f32 v228, v228, v239, v239
	v_fma_f32 v230, v230, v239, v239
	v_fma_f32 v232, v232, v239, v239
	v_fma_f32 v234, v234, v239, v239
	v_rcp_f32_e32 v228, v228
	v_rcp_f32_e32 v230, v230
	v_rcp_f32_e32 v232, v232
	v_rcp_f32_e32 v234, v234
	v_mul_f32_e32 v100, v229, v228
	v_mul_f32_e32 v101, v231, v230
	v_mul_f32_e32 v102, v233, v232
	v_mul_f32_e32 v99, v235, v234
	s_nop 0
	v_cvt_pk_bf16_f32 v96, v108, v109
	v_cvt_pk_bf16_f32 v97, v110, v106
	v_cvt_pk_bf16_f32 v98, v100, v101
	v_cvt_pk_bf16_f32 v99, v102, v99
	global_store_dwordx4 v[112:113], v[96:99], off offset:1024
	s_nop 1
	s_nop 0
	s_nop 0
	v_mul_f32_e32 v240, 0xbfb8aa3b, v158
	v_mul_f32_e32 v241, v158, v158
	v_rcp_f32_e32 v241, v241
	v_mul_f32_e32 v220, v240, v92
	v_mul_f32_e32 v222, v240, v93
	v_mul_f32_e32 v224, v240, v94
	v_mul_f32_e32 v226, v240, v95
	v_mul_f32_e32 v221, v92, v88
	v_mul_f32_e32 v223, v93, v89
	v_mul_f32_e32 v225, v94, v90
	v_mul_f32_e32 v227, v95, v91
	v_exp_f32_e32 v220, v220
	v_exp_f32_e32 v222, v222
	v_exp_f32_e32 v224, v224
	v_exp_f32_e32 v226, v226
	v_fma_f32 v220, v220, v241, v241
	v_fma_f32 v222, v222, v241, v241
	v_fma_f32 v224, v224, v241, v241
	v_fma_f32 v226, v226, v241, v241
	v_rcp_f32_e32 v220, v220
	v_rcp_f32_e32 v222, v222
	v_rcp_f32_e32 v224, v224
	v_rcp_f32_e32 v226, v226
	v_mul_f32_e32 v92, v221, v220
	v_mul_f32_e32 v93, v223, v222
	v_mul_f32_e32 v94, v225, v224
	v_mul_f32_e32 v90, v227, v226
	s_nop 0
	s_nop 0
	s_nop 0
	v_mul_f32_e32 v228, v240, v84
	v_mul_f32_e32 v230, v240, v85
	v_mul_f32_e32 v232, v240, v86
	v_mul_f32_e32 v234, v240, v87
	v_mul_f32_e32 v229, v84, v80
	v_mul_f32_e32 v231, v85, v81
	v_mul_f32_e32 v233, v86, v82
	v_mul_f32_e32 v235, v87, v83
	v_exp_f32_e32 v228, v228
	v_exp_f32_e32 v230, v230
	v_exp_f32_e32 v232, v232
	v_exp_f32_e32 v234, v234
	v_fma_f32 v228, v228, v241, v241
	v_fma_f32 v230, v230, v241, v241
	v_fma_f32 v232, v232, v241, v241
	v_fma_f32 v234, v234, v241, v241
	v_rcp_f32_e32 v228, v228
	v_rcp_f32_e32 v230, v230
	v_rcp_f32_e32 v232, v232
	v_rcp_f32_e32 v234, v234
	v_mul_f32_e32 v84, v229, v228
	v_mul_f32_e32 v85, v231, v230
	v_mul_f32_e32 v86, v233, v232
	v_mul_f32_e32 v83, v235, v234
	s_nop 0
	v_cvt_pk_bf16_f32 v80, v92, v93
	v_cvt_pk_bf16_f32 v81, v94, v90
	v_cvt_pk_bf16_f32 v82, v84, v85
	v_cvt_pk_bf16_f32 v83, v86, v83
	global_store_dwordx4 v[112:113], v[80:83], off offset:2048
	s_nop 1
	s_nop 0
	s_nop 0
	v_mul_f32_e32 v242, 0xbfb8aa3b, v154
	v_mul_f32_e32 v243, v154, v154
	v_rcp_f32_e32 v243, v243
	v_mul_f32_e32 v220, v242, v76
	v_mul_f32_e32 v222, v242, v77
	v_mul_f32_e32 v224, v242, v78
	v_mul_f32_e32 v226, v242, v79
	v_mul_f32_e32 v221, v76, v72
	v_mul_f32_e32 v223, v77, v73
	v_mul_f32_e32 v225, v78, v74
	v_mul_f32_e32 v227, v79, v75
	v_exp_f32_e32 v220, v220
	v_exp_f32_e32 v222, v222
	v_exp_f32_e32 v224, v224
	v_exp_f32_e32 v226, v226
	v_fma_f32 v220, v220, v243, v243
	v_fma_f32 v222, v222, v243, v243
	v_fma_f32 v224, v224, v243, v243
	v_fma_f32 v226, v226, v243, v243
	v_rcp_f32_e32 v220, v220
	v_rcp_f32_e32 v222, v222
	v_rcp_f32_e32 v224, v224
	v_rcp_f32_e32 v226, v226
	v_mul_f32_e32 v76, v221, v220
	v_mul_f32_e32 v77, v223, v222
	v_mul_f32_e32 v78, v225, v224
	v_mul_f32_e32 v74, v227, v226
	s_nop 0
	s_nop 0
	s_nop 0
	v_mul_f32_e32 v228, v242, v68
	v_mul_f32_e32 v230, v242, v69
	v_mul_f32_e32 v232, v242, v70
	v_mul_f32_e32 v234, v242, v71
	v_mul_f32_e32 v229, v68, v64
	v_mul_f32_e32 v231, v69, v65
	v_mul_f32_e32 v233, v70, v66
	v_mul_f32_e32 v235, v71, v67
	v_exp_f32_e32 v228, v228
	v_exp_f32_e32 v230, v230
	v_exp_f32_e32 v232, v232
	v_exp_f32_e32 v234, v234
	v_fma_f32 v228, v228, v243, v243
	v_fma_f32 v230, v230, v243, v243
	v_fma_f32 v232, v232, v243, v243
	v_fma_f32 v234, v234, v243, v243
	v_rcp_f32_e32 v228, v228
	v_rcp_f32_e32 v230, v230
	v_rcp_f32_e32 v232, v232
	v_rcp_f32_e32 v234, v234
	v_mul_f32_e32 v68, v229, v228
	v_mul_f32_e32 v69, v231, v230
	v_mul_f32_e32 v70, v233, v232
	v_mul_f32_e32 v67, v235, v234
	s_nop 0
	v_cvt_pk_bf16_f32 v64, v76, v77
	v_cvt_pk_bf16_f32 v65, v78, v74
	v_cvt_pk_bf16_f32 v66, v68, v69
	v_cvt_pk_bf16_f32 v67, v70, v67
	global_store_dwordx4 v[112:113], v[64:67], off offset:3072
	s_nop 1
	v_or_b32_e32 v66, s9, v157
	v_lshlrev_b32_e32 v168, 6, v66
	s_nop 0
	v_mul_f32_e32 v244, 0xbfb8aa3b, v152
	v_mul_f32_e32 v245, v152, v152
	v_rcp_f32_e32 v245, v245
	v_mul_f32_e32 v220, v244, v60
	v_mul_f32_e32 v222, v244, v61
	v_mul_f32_e32 v224, v244, v62
	v_mul_f32_e32 v226, v244, v63
	v_mul_f32_e32 v221, v60, v56
	v_mul_f32_e32 v223, v61, v57
	v_mul_f32_e32 v225, v62, v58
	v_mul_f32_e32 v227, v63, v59
	v_exp_f32_e32 v220, v220
	v_exp_f32_e32 v222, v222
	v_exp_f32_e32 v224, v224
	v_exp_f32_e32 v226, v226
	v_fma_f32 v220, v220, v245, v245
	v_fma_f32 v222, v222, v245, v245
	v_fma_f32 v224, v224, v245, v245
	v_fma_f32 v226, v226, v245, v245
	v_rcp_f32_e32 v220, v220
	v_rcp_f32_e32 v222, v222
	v_rcp_f32_e32 v224, v224
	v_rcp_f32_e32 v226, v226
	v_mul_f32_e32 v60, v221, v220
	v_mul_f32_e32 v61, v223, v222
	v_mul_f32_e32 v62, v225, v224
	v_mul_f32_e32 v58, v227, v226
	s_nop 0
	s_nop 0
	s_nop 0
	v_mul_f32_e32 v228, v244, v52
	v_mul_f32_e32 v230, v244, v53
	v_mul_f32_e32 v232, v244, v54
	v_mul_f32_e32 v234, v244, v55
	v_mul_f32_e32 v229, v52, v48
	v_mul_f32_e32 v231, v53, v49
	v_mul_f32_e32 v233, v54, v50
	v_mul_f32_e32 v235, v55, v51
	v_exp_f32_e32 v228, v228
	v_exp_f32_e32 v230, v230
	v_exp_f32_e32 v232, v232
	v_exp_f32_e32 v234, v234
	v_fma_f32 v228, v228, v245, v245
	v_fma_f32 v230, v230, v245, v245
	v_fma_f32 v232, v232, v245, v245
	v_fma_f32 v234, v234, v245, v245
	v_rcp_f32_e32 v228, v228
	v_rcp_f32_e32 v230, v230
	v_rcp_f32_e32 v232, v232
	v_rcp_f32_e32 v234, v234
	v_mul_f32_e32 v52, v229, v228
	v_mul_f32_e32 v53, v231, v230
	v_mul_f32_e32 v54, v233, v232
	v_mul_f32_e32 v48, v235, v234
	v_cvt_pk_bf16_f32 v50, v60, v61
	v_cvt_pk_bf16_f32 v51, v62, v58
	v_cvt_pk_bf16_f32 v52, v52, v53
	s_nop 0
	v_cvt_pk_bf16_f32 v53, v54, v48
	v_lshl_add_u64 v[48:49], s[0:1], 0, v[168:169]
	v_lshl_add_u64 v[48:49], v[48:49], 0, v[144:145]
	global_store_dwordx4 v[48:49], v[50:53], off
	s_mov_b64 s[0:1], -1
	s_nop 0
	s_nop 0
	s_nop 0
	v_mul_f32_e32 v246, 0xbfb8aa3b, v150
	v_mul_f32_e32 v247, v150, v150
	v_rcp_f32_e32 v247, v247
	v_mul_f32_e32 v220, v246, v44
	v_mul_f32_e32 v222, v246, v45
	v_mul_f32_e32 v224, v246, v46
	v_mul_f32_e32 v226, v246, v47
	v_mul_f32_e32 v221, v44, v40
	v_mul_f32_e32 v223, v45, v41
	v_mul_f32_e32 v225, v46, v42
	v_mul_f32_e32 v227, v47, v43
	v_exp_f32_e32 v220, v220
	v_exp_f32_e32 v222, v222
	v_exp_f32_e32 v224, v224
	v_exp_f32_e32 v226, v226
	v_fma_f32 v220, v220, v247, v247
	v_fma_f32 v222, v222, v247, v247
	v_fma_f32 v224, v224, v247, v247
	v_fma_f32 v226, v226, v247, v247
	v_rcp_f32_e32 v220, v220
	v_rcp_f32_e32 v222, v222
	v_rcp_f32_e32 v224, v224
	v_rcp_f32_e32 v226, v226
	v_mul_f32_e32 v44, v221, v220
	v_mul_f32_e32 v45, v223, v222
	v_mul_f32_e32 v46, v225, v224
	v_mul_f32_e32 v42, v227, v226
	s_nop 0
	s_nop 0
	s_nop 0
	v_mul_f32_e32 v228, v246, v36
	v_mul_f32_e32 v230, v246, v37
	v_mul_f32_e32 v232, v246, v38
	v_mul_f32_e32 v234, v246, v39
	v_mul_f32_e32 v229, v36, v32
	v_mul_f32_e32 v231, v37, v33
	v_mul_f32_e32 v233, v38, v34
	v_mul_f32_e32 v235, v39, v35
	v_exp_f32_e32 v228, v228
	v_exp_f32_e32 v230, v230
	v_exp_f32_e32 v232, v232
	v_exp_f32_e32 v234, v234
	v_fma_f32 v228, v228, v247, v247
	v_fma_f32 v230, v230, v247, v247
	v_fma_f32 v232, v232, v247, v247
	v_fma_f32 v234, v234, v247, v247
	v_rcp_f32_e32 v228, v228
	v_rcp_f32_e32 v230, v230
	v_rcp_f32_e32 v232, v232
	v_rcp_f32_e32 v234, v234
	v_mul_f32_e32 v36, v229, v228
	v_mul_f32_e32 v37, v231, v230
	v_mul_f32_e32 v38, v233, v232
	v_mul_f32_e32 v35, v235, v234
	s_nop 0
	v_cvt_pk_bf16_f32 v32, v44, v45
	v_cvt_pk_bf16_f32 v33, v46, v42
	v_cvt_pk_bf16_f32 v34, v36, v37
	v_cvt_pk_bf16_f32 v35, v38, v35
	global_store_dwordx4 v[48:49], v[32:35], off offset:1024
	s_nop 1
	s_nop 0
	s_nop 0
	v_mul_f32_e32 v248, 0xbfb8aa3b, v148
	v_mul_f32_e32 v249, v148, v148
	v_rcp_f32_e32 v249, v249
	v_mul_f32_e32 v220, v248, v28
	v_mul_f32_e32 v222, v248, v29
	v_mul_f32_e32 v224, v248, v30
	v_mul_f32_e32 v226, v248, v31
	v_mul_f32_e32 v221, v28, v24
	v_mul_f32_e32 v223, v29, v25
	v_mul_f32_e32 v225, v30, v26
	v_mul_f32_e32 v227, v31, v27
	v_exp_f32_e32 v220, v220
	v_exp_f32_e32 v222, v222
	v_exp_f32_e32 v224, v224
	v_exp_f32_e32 v226, v226
	v_fma_f32 v220, v220, v249, v249
	v_fma_f32 v222, v222, v249, v249
	v_fma_f32 v224, v224, v249, v249
	v_fma_f32 v226, v226, v249, v249
	v_rcp_f32_e32 v220, v220
	v_rcp_f32_e32 v222, v222
	v_rcp_f32_e32 v224, v224
	v_rcp_f32_e32 v226, v226
	v_mul_f32_e32 v28, v221, v220
	v_mul_f32_e32 v29, v223, v222
	v_mul_f32_e32 v30, v225, v224
	v_mul_f32_e32 v26, v227, v226
	s_nop 0
	s_nop 0
	s_nop 0
	v_mul_f32_e32 v228, v248, v20
	v_mul_f32_e32 v230, v248, v21
	v_mul_f32_e32 v232, v248, v22
	v_mul_f32_e32 v234, v248, v23
	v_mul_f32_e32 v229, v20, v16
	v_mul_f32_e32 v231, v21, v17
	v_mul_f32_e32 v233, v22, v18
	v_mul_f32_e32 v235, v23, v19
	v_exp_f32_e32 v228, v228
	v_exp_f32_e32 v230, v230
	v_exp_f32_e32 v232, v232
	v_exp_f32_e32 v234, v234
	v_fma_f32 v228, v228, v249, v249
	v_fma_f32 v230, v230, v249, v249
	v_fma_f32 v232, v232, v249, v249
	v_fma_f32 v234, v234, v249, v249
	v_rcp_f32_e32 v228, v228
	v_rcp_f32_e32 v230, v230
	v_rcp_f32_e32 v232, v232
	v_rcp_f32_e32 v234, v234
	v_mul_f32_e32 v20, v229, v228
	v_mul_f32_e32 v21, v231, v230
	v_mul_f32_e32 v22, v233, v232
	v_mul_f32_e32 v19, v235, v234
	s_nop 0
	v_cvt_pk_bf16_f32 v16, v28, v29
	v_cvt_pk_bf16_f32 v17, v30, v26
	v_cvt_pk_bf16_f32 v18, v20, v21
	v_cvt_pk_bf16_f32 v19, v22, v19
	global_store_dwordx4 v[48:49], v[16:19], off offset:2048
	s_nop 1
	s_nop 0
	s_nop 0
	v_mul_f32_e32 v250, 0xbfb8aa3b, v146
	v_mul_f32_e32 v251, v146, v146
	v_rcp_f32_e32 v251, v251
	v_mul_f32_e32 v220, v250, v12
	v_mul_f32_e32 v222, v250, v13
	v_mul_f32_e32 v224, v250, v14
	v_mul_f32_e32 v226, v250, v15
	v_mul_f32_e32 v221, v12, v8
	v_mul_f32_e32 v223, v13, v9
	v_mul_f32_e32 v225, v14, v10
	v_mul_f32_e32 v227, v15, v11
	v_exp_f32_e32 v220, v220
	v_exp_f32_e32 v222, v222
	v_exp_f32_e32 v224, v224
	v_exp_f32_e32 v226, v226
	v_fma_f32 v220, v220, v251, v251
	v_fma_f32 v222, v222, v251, v251
	v_fma_f32 v224, v224, v251, v251
	v_fma_f32 v226, v226, v251, v251
	v_rcp_f32_e32 v220, v220
	v_rcp_f32_e32 v222, v222
	v_rcp_f32_e32 v224, v224
	v_rcp_f32_e32 v226, v226
	v_mul_f32_e32 v12, v221, v220
	v_mul_f32_e32 v13, v223, v222
	v_mul_f32_e32 v14, v225, v224
	v_mul_f32_e32 v10, v227, v226
	s_nop 0
	s_nop 0
	s_nop 0
	v_mul_f32_e32 v228, v250, v4
	v_mul_f32_e32 v230, v250, v5
	v_mul_f32_e32 v232, v250, v6
	v_mul_f32_e32 v234, v250, v7
	v_mul_f32_e32 v229, v4, v0
	v_mul_f32_e32 v231, v5, v1
	v_mul_f32_e32 v233, v6, v2
	v_mul_f32_e32 v235, v7, v3
	v_exp_f32_e32 v228, v228
	v_exp_f32_e32 v230, v230
	v_exp_f32_e32 v232, v232
	v_exp_f32_e32 v234, v234
	v_fma_f32 v228, v228, v251, v251
	v_fma_f32 v230, v230, v251, v251
	v_fma_f32 v232, v232, v251, v251
	v_fma_f32 v234, v234, v251, v251
	v_rcp_f32_e32 v228, v228
	v_rcp_f32_e32 v230, v230
	v_rcp_f32_e32 v232, v232
	v_rcp_f32_e32 v234, v234
	v_mul_f32_e32 v4, v229, v228
	v_mul_f32_e32 v5, v231, v230
	v_mul_f32_e32 v6, v233, v232
	v_mul_f32_e32 v3, v235, v234
	s_nop 0
	v_cvt_pk_bf16_f32 v0, v12, v13
	v_cvt_pk_bf16_f32 v1, v14, v10
	v_cvt_pk_bf16_f32 v2, v4, v5
	v_cvt_pk_bf16_f32 v3, v6, v3
	global_store_dwordx4 v[48:49], v[0:3], off offset:3072
	s_cbranch_vccnz .LBB0_1061
	s_andn2_b64 vcc, exec, s[4:5]
	s_cbranch_vccnz .LBB0_1060
	s_barrier
	s_branch .LBB0_1060

.LBB0_1072:
	s_nop 0
	s_nop 0
	s_nop 0
	s_nop 0
	s_nop 0
	s_nop 0
	s_nop 0
	s_nop 0
	s_nop 0
	s_nop 0
	s_nop 0
	s_nop 0
	s_nop 0
	s_nop 0
	s_nop 0
	s_nop 0
	s_nop 0
	s_nop 0
	s_nop 0
	s_nop 0
	s_nop 0
	s_nop 0
	s_nop 0
	s_nop 0
	s_nop 0
	s_nop 0
	s_nop 0
	s_nop 0
	s_nop 0
	s_nop 0
	s_nop 0
	s_nop 0
	s_nop 0
	s_nop 0
	s_nop 0
	s_nop 0
	s_nop 0
	s_nop 0
	s_nop 0
	s_nop 0
	s_nop 0
	s_nop 0
	s_nop 0
	s_nop 0
	s_nop 0
	s_nop 0
	s_nop 0
	s_nop 0
	s_nop 0
	s_nop 0
	s_nop 0
	s_nop 0
	s_nop 0
	s_nop 0
	s_nop 0
	s_nop 0
	s_getreg_b32 s2, hwreg(HW_REG_XCC_ID, 0, 4)
	s_waitcnt vmcnt(0)
	s_barrier
	s_mov_b64 s[0:1], exec
	v_readlane_b32 s4, v252, 8
	v_readlane_b32 s5, v252, 9
	s_and_b64 s[4:5], s[0:1], s[4:5]
	s_mov_b64 exec, s[4:5]
	s_cbranch_execz .LBB0_1124
	v_readlane_b32 s3, v254, 55
	s_waitcnt vmcnt(0) expcnt(0) lgkmcnt(0)
	s_and_b32 s8, s2, 15
	v_mov_b32_e32 v0, s3
	ds_read_b32 v2, v0
	v_readlane_b32 s3, v254, 56
	s_waitcnt lgkmcnt(0)
	v_cmp_ne_u32_e32 vcc, 0, v2
	v_mov_b32_e32 v0, s3
	ds_read_b32 v0, v0
	s_cbranch_vccnz .LBB0_1088
	s_mov_b32 s9, 1
	s_branch .LBB0_1076
